# no store-draining wait between the Win and Z GEMM phases (stacked on v137)
# speedup vs baseline: 1.0105x; 1.0010x over previous
.LBB0_401:
	s_and_b64 vcc, exec, s[76:77]
	s_cbranch_vccnz .LBB0_232
	s_barrier
	s_branch .LBB0_232
.LBB0_403:
	s_barrier
.LBB0_404:
	v_readlane_b32 s0, v253, 52
	v_readlane_b32 s1, v253, 53
	s_andn2_b64 vcc, exec, s[0:1]
	v_mbcnt_lo_u32_b32 v8, -1, 0
	v_mbcnt_hi_u32_b32 v8, -1, v8
	s_cbranch_vccnz .LBB0_432
	v_readlane_b32 s0, v253, 57
	v_readlane_b32 s1, v253, 58
	s_andn2_b64 vcc, exec, s[0:1]
	v_readlane_b32 s0, v254, 28
	s_cbranch_vccnz .LBB0_407
	v_readlane_b32 s0, v253, 60
